# stack of bit-exact micro-changes: v19 + attention-B gain-load hoist + final-norm bf16 row loads without nt
# speedup vs baseline: 1.0044x; 1.0006x over previous
.LBB0_367:
	s_or_b64 exec, exec, s[0:1]
	v_lshl_add_u64 v[28:29], s[40:41], 0, v[16:17]
	global_load_dwordx2 v[72:73], v[28:29], off
	global_load_dwordx2 v[74:75], v[28:29], off offset:512
	global_load_dwordx2 v[76:77], v[28:29], off offset:1024
	global_load_dwordx2 v[78:79], v[28:29], off offset:1536
	global_load_dwordx2 v[80:81], v[28:29], off offset:2048
	global_load_dwordx2 v[82:83], v[28:29], off offset:2560
	global_load_dwordx2 v[84:85], v[28:29], off offset:3072
	global_load_dwordx2 v[86:87], v[28:29], off offset:3584
	s_waitcnt vmcnt(8)
	ds_bpermute_b32 v32, v1, v23
	v_lshl_add_u64 v[12:13], v[12:13], 0, s[26:27]
	v_lshl_add_u64 v[16:17], v[16:17], 0, s[38:39]
	s_waitcnt lgkmcnt(0)
	v_add_f32_e32 v23, v23, v32
	ds_bpermute_b32 v32, v18, v23
	s_waitcnt lgkmcnt(0)
	v_add_f32_e32 v23, v23, v32
	ds_bpermute_b32 v32, v19, v23
	s_waitcnt lgkmcnt(0)
	v_add_f32_e32 v23, v23, v32
	ds_bpermute_b32 v32, v20, v23
	s_waitcnt lgkmcnt(0)
	v_add_f32_e32 v23, v23, v32
	ds_bpermute_b32 v32, v21, v23
	s_waitcnt lgkmcnt(0)
	v_add_f32_e32 v23, v23, v32
	ds_bpermute_b32 v32, v22, v23
	s_waitcnt lgkmcnt(0)
	v_add_f32_e32 v23, v23, v32
	v_fmamk_f32 v23, v23, 0x3a000000, v216
	v_mul_f32_e32 v32, 0x4b800000, v23
	v_cmp_gt_f32_e64 s[4:5], s65, v23
	s_nop 1
	v_cndmask_b32_e64 v23, v23, v32, s[4:5]
	v_rsq_f32_e32 v23, v23
	s_nop 0
	v_mul_f32_e32 v32, 0x45800000, v23
	v_cndmask_b32_e64 v32, v23, v32, s[4:5]
	s_waitcnt vmcnt(7)
	v_lshlrev_b32_e32 v34, 16, v72
	v_and_b32_e32 v35, 0xffff0000, v72
	v_lshlrev_b32_e32 v30, 16, v73
	v_and_b32_e32 v31, 0xffff0000, v73
	v_pk_mul_f32 v[34:35], v[32:33], v[34:35] op_sel_hi:[0,1]
	v_pk_mul_f32 v[30:31], v[32:33], v[30:31] op_sel_hi:[0,1]
	v_pk_mul_f32 v[26:27], v[42:43], v[30:31]
	v_pk_mul_f32 v[24:25], v[40:41], v[34:35]
	global_store_dwordx4 v[14:15], v[24:27], off offset:-4096 nt
	s_waitcnt vmcnt(7)
	v_lshlrev_b32_e32 v34, 16, v74
	v_and_b32_e32 v35, 0xffff0000, v74
	v_lshlrev_b32_e32 v30, 16, v75
	v_and_b32_e32 v31, 0xffff0000, v75
	v_pk_mul_f32 v[34:35], v[32:33], v[34:35] op_sel_hi:[0,1]
	v_pk_mul_f32 v[30:31], v[32:33], v[30:31] op_sel_hi:[0,1]
	v_pk_mul_f32 v[26:27], v[46:47], v[30:31]
	v_pk_mul_f32 v[24:25], v[44:45], v[34:35]
	global_store_dwordx4 v[14:15], v[24:27], off offset:-3072 nt
	s_waitcnt vmcnt(7)
	v_lshlrev_b32_e32 v34, 16, v76
	v_and_b32_e32 v35, 0xffff0000, v76
	v_lshlrev_b32_e32 v30, 16, v77
	v_and_b32_e32 v31, 0xffff0000, v77
	v_pk_mul_f32 v[34:35], v[32:33], v[34:35] op_sel_hi:[0,1]
	v_pk_mul_f32 v[30:31], v[32:33], v[30:31] op_sel_hi:[0,1]
	v_pk_mul_f32 v[26:27], v[50:51], v[30:31]
	v_pk_mul_f32 v[24:25], v[48:49], v[34:35]
	global_store_dwordx4 v[14:15], v[24:27], off offset:-2048 nt
	s_waitcnt vmcnt(7)
	v_lshlrev_b32_e32 v34, 16, v78
	v_and_b32_e32 v35, 0xffff0000, v78
	v_lshlrev_b32_e32 v30, 16, v79
	v_and_b32_e32 v31, 0xffff0000, v79
	v_pk_mul_f32 v[34:35], v[32:33], v[34:35] op_sel_hi:[0,1]
	v_pk_mul_f32 v[30:31], v[32:33], v[30:31] op_sel_hi:[0,1]
	v_pk_mul_f32 v[26:27], v[54:55], v[30:31]
	v_pk_mul_f32 v[24:25], v[52:53], v[34:35]
	global_store_dwordx4 v[14:15], v[24:27], off offset:-1024 nt
	s_waitcnt vmcnt(7)
	v_lshlrev_b32_e32 v34, 16, v80
	v_and_b32_e32 v35, 0xffff0000, v80
	v_lshlrev_b32_e32 v30, 16, v81
	v_and_b32_e32 v31, 0xffff0000, v81
	v_pk_mul_f32 v[34:35], v[32:33], v[34:35] op_sel_hi:[0,1]
	v_pk_mul_f32 v[30:31], v[32:33], v[30:31] op_sel_hi:[0,1]
	v_pk_mul_f32 v[26:27], v[58:59], v[30:31]
	v_pk_mul_f32 v[24:25], v[56:57], v[34:35]
	global_store_dwordx4 v[14:15], v[24:27], off nt
	s_waitcnt vmcnt(7)
	v_lshlrev_b32_e32 v34, 16, v82
	v_and_b32_e32 v35, 0xffff0000, v82
	v_lshlrev_b32_e32 v30, 16, v83
	v_and_b32_e32 v31, 0xffff0000, v83
	v_pk_mul_f32 v[34:35], v[32:33], v[34:35] op_sel_hi:[0,1]
	v_pk_mul_f32 v[30:31], v[32:33], v[30:31] op_sel_hi:[0,1]
	v_pk_mul_f32 v[26:27], v[62:63], v[30:31]
	v_pk_mul_f32 v[24:25], v[60:61], v[34:35]
	global_store_dwordx4 v[14:15], v[24:27], off offset:1024 nt
	s_waitcnt vmcnt(7)
	v_lshlrev_b32_e32 v34, 16, v84
	v_and_b32_e32 v35, 0xffff0000, v84
	v_lshlrev_b32_e32 v30, 16, v85
	v_and_b32_e32 v31, 0xffff0000, v85
	v_pk_mul_f32 v[34:35], v[32:33], v[34:35] op_sel_hi:[0,1]
	v_pk_mul_f32 v[30:31], v[32:33], v[30:31] op_sel_hi:[0,1]
	v_pk_mul_f32 v[26:27], v[66:67], v[30:31]
	v_pk_mul_f32 v[24:25], v[64:65], v[34:35]
	global_store_dwordx4 v[14:15], v[24:27], off offset:2048 nt
	s_waitcnt vmcnt(7)
	v_lshlrev_b32_e32 v34, 16, v86
	v_and_b32_e32 v35, 0xffff0000, v86
	v_lshlrev_b32_e32 v30, 16, v87
	v_and_b32_e32 v31, 0xffff0000, v87
	v_pk_mul_f32 v[34:35], v[32:33], v[34:35] op_sel_hi:[0,1]
	v_pk_mul_f32 v[30:31], v[32:33], v[30:31] op_sel_hi:[0,1]
	v_pk_mul_f32 v[26:27], v[70:71], v[30:31]
	v_pk_mul_f32 v[24:25], v[68:69], v[34:35]
	global_store_dwordx4 v[14:15], v[24:27], off offset:3072 nt
	v_lshl_add_u64 v[14:15], v[14:15], 0, s[24:25]
	s_add_i32 s2, s2, s60
	s_cmpk_gt_i32 s2, 0x3fff
	s_cbranch_scc1 .LBB0_370
